# final seam: software prefetch of next row pair into staging regs (overlaps load latency with compute); kept store-data hazard slot
# speedup vs baseline: 1.0062x; 1.0062x over previous
.LBB0_1208:
	s_or_b64 exec, exec, s[0:1]
	s_waitcnt lgkmcnt(0)
	s_barrier
	s_and_saveexec_b64 s[0:1], s[86:87]
	s_cbranch_execz .LBB0_1213
	s_add_u32 s0, s36, 0x2000
	s_addc_u32 s1, s37, 0
	global_load_dwordx4 v[0:3], v150, s[0:1]
	global_load_dwordx4 v[4:7], v152, s[0:1]
	global_load_dwordx4 v[8:11], v154, s[0:1]
	global_load_dwordx4 v[12:15], v144, s[0:1]
	v_mbcnt_hi_u32_b32 v16, -1, v167
	v_and_b32_e32 v17, 64, v16
	v_add_u32_e32 v17, 64, v17
	v_xor_b32_e32 v18, 32, v16
	v_cmp_lt_i32_e32 vcc, v18, v17
	s_mov_b64 s[4:5], 0x1000
	s_mov_b64 s[0:1], 0x15e22e00
	v_cndmask_b32_e32 v18, v16, v18, vcc
	v_lshlrev_b32_e32 v37, 2, v18
	v_xor_b32_e32 v18, 16, v16
	v_cmp_lt_i32_e32 vcc, v18, v17
	v_mov_b32_e32 v145, 0
	s_mov_b64 s[2:3], 0x2000
	v_cndmask_b32_e32 v18, v16, v18, vcc
	v_lshlrev_b32_e32 v74, 2, v18
	v_xor_b32_e32 v18, 8, v16
	v_cmp_lt_i32_e32 vcc, v18, v17
	v_mov_b32_e32 v79, -1
	s_mov_b64 s[6:7], 0
	v_cndmask_b32_e32 v18, v16, v18, vcc
	v_lshlrev_b32_e32 v75, 2, v18
	v_xor_b32_e32 v18, 4, v16
	v_cmp_lt_i32_e32 vcc, v18, v17
	s_mov_b32 s11, 0xed400000
	s_movk_i32 s12, 0x1fff
	v_cndmask_b32_e32 v18, v16, v18, vcc
	v_lshlrev_b32_e32 v76, 2, v18
	v_xor_b32_e32 v18, 2, v16
	v_cmp_lt_i32_e32 vcc, v18, v17
	s_mov_b64 s[8:9], 0x3154000
	s_mov_b32 s10, 0x3a800000
	v_cndmask_b32_e32 v18, v16, v18, vcc
	v_lshlrev_b32_e32 v77, 2, v18
	v_xor_b32_e32 v18, 1, v16
	v_cmp_lt_i32_e32 vcc, v18, v17
	s_mov_b32 s13, 0x800000
	v_mov_b32_e32 v36, 0x358637bd
	v_cndmask_b32_e32 v16, v16, v18, vcc
	v_lshlrev_b32_e32 v78, 2, v16
	v_lshlrev_b64 v[16:17], 12, v[148:149]
	v_lshl_or_b32 v16, v147, 4, v16
	v_lshl_add_u64 v[16:17], s[30:31], 0, v[16:17]
	v_lshl_add_u64 v[32:33], v[16:17], 0, s[4:5]
	v_lshlrev_b64 v[16:17], 11, v[148:149]
	v_lshl_or_b32 v16, v147, 3, v16
	v_lshl_add_u64 v[16:17], s[34:35], 0, v[16:17]
	v_lshl_add_u64 v[34:35], v[16:17], 0, s[0:1]
	v_mov_b32_e32 v16, v145
	v_mov_b32_e32 v17, v145
	v_mov_b32_e32 v18, v145
	v_mov_b32_e32 v19, v145
	v_mov_b32_e32 v20, v145
	v_mov_b32_e32 v21, v145
	v_mov_b32_e32 v22, v145
	v_mov_b32_e32 v23, v145
	v_mov_b32_e32 v24, v145
	v_mov_b32_e32 v25, v145
	v_mov_b32_e32 v26, v145
	v_mov_b32_e32 v27, v145
	v_mov_b32_e32 v28, v145
	v_mov_b32_e32 v29, v145
	v_mov_b32_e32 v30, v145
	v_mov_b32_e32 v31, v145
	v_add_co_u32_e32 v198, vcc, s11, v34
	global_load_dwordx2 v[200:201], v[34:35], off offset:-3584
	global_load_dwordx2 v[202:203], v[34:35], off offset:-3072
	global_load_dwordx2 v[204:205], v[34:35], off offset:-2560
	global_load_dwordx2 v[206:207], v[34:35], off offset:-2048
	v_addc_co_u32_e32 v199, vcc, -1, v35, vcc
	global_load_dwordx2 v[208:209], v[198:199], off offset:-3584
	global_load_dwordx2 v[210:211], v[198:199], off offset:-3072
	global_load_dwordx2 v[212:213], v[198:199], off offset:-2560
	global_load_dwordx2 v[214:215], v[198:199], off offset:-2048
	global_load_dwordx2 v[216:217], v[34:35], off offset:-1536
	global_load_dwordx2 v[218:219], v[34:35], off offset:-1024
	global_load_dwordx2 v[220:221], v[34:35], off offset:-512
	global_load_dwordx2 v[222:223], v[34:35], off
	global_load_dwordx2 v[224:225], v[198:199], off offset:-1536
	global_load_dwordx2 v[226:227], v[198:199], off offset:-1024
	global_load_dwordx2 v[228:229], v[198:199], off offset:-512
	global_load_dwordx2 v[230:231], v[198:199], off
	s_branch .LBB0_1211
.LBB0_1210:
	s_or_b64 exec, exec, s[0:1]
	s_waitcnt vmcnt(0)
	v_mov_b64_e32 v[56:57], v[200:201]
	v_mov_b64_e32 v[50:51], v[202:203]
	v_mov_b64_e32 v[48:49], v[204:205]
	v_mov_b64_e32 v[44:45], v[206:207]
	v_mov_b64_e32 v[60:61], v[208:209]
	v_mov_b64_e32 v[58:59], v[210:211]
	v_mov_b64_e32 v[54:55], v[212:213]
	v_mov_b64_e32 v[52:53], v[214:215]
	v_mov_b64_e32 v[46:47], v[216:217]
	v_mov_b64_e32 v[42:43], v[218:219]
	v_mov_b64_e32 v[40:41], v[220:221]
	v_mov_b64_e32 v[38:39], v[222:223]
	v_mov_b64_e32 v[72:73], v[224:225]
	v_mov_b64_e32 v[70:71], v[226:227]
	v_mov_b64_e32 v[68:69], v[228:229]
	v_mov_b64_e32 v[66:67], v[230:231]
	v_lshl_add_u64 v[34:35], v[34:35], 0, s[4:5]
	v_add_u32_e32 v197, 2, v148
	v_cmp_lt_i32_e32 vcc, v197, v186
	s_and_saveexec_b64 s[14:15], vcc
	s_cbranch_execz .Ls3_nopf
	v_add_co_u32_e32 v198, vcc, s11, v34
	global_load_dwordx2 v[200:201], v[34:35], off offset:-3584
	global_load_dwordx2 v[202:203], v[34:35], off offset:-3072
	global_load_dwordx2 v[204:205], v[34:35], off offset:-2560
	global_load_dwordx2 v[206:207], v[34:35], off offset:-2048
	v_addc_co_u32_e32 v199, vcc, -1, v35, vcc
	global_load_dwordx2 v[208:209], v[198:199], off offset:-3584
	global_load_dwordx2 v[210:211], v[198:199], off offset:-3072
	global_load_dwordx2 v[212:213], v[198:199], off offset:-2560
	global_load_dwordx2 v[214:215], v[198:199], off offset:-2048
	global_load_dwordx2 v[216:217], v[34:35], off offset:-1536
	global_load_dwordx2 v[218:219], v[34:35], off offset:-1024
	global_load_dwordx2 v[220:221], v[34:35], off offset:-512
	global_load_dwordx2 v[222:223], v[34:35], off
	global_load_dwordx2 v[224:225], v[198:199], off offset:-1536
	global_load_dwordx2 v[226:227], v[198:199], off offset:-1024
	global_load_dwordx2 v[228:229], v[198:199], off offset:-512
	global_load_dwordx2 v[230:231], v[198:199], off
.Ls3_nopf:
	s_or_b64 exec, exec, s[14:15]
	v_and_b32_e32 v81, 0xffff0000, v60
	v_and_b32_e32 v89, 0xffff0000, v72
	v_lshlrev_b32_e32 v80, 16, v60
	v_lshlrev_b32_e32 v88, 16, v72
	v_mov_b32_e32 v102, v89
	v_mov_b32_e32 v103, v81
	v_lshlrev_b32_e32 v82, 16, v61
	v_lshlrev_b32_e32 v72, 16, v73
	v_mov_b32_e32 v100, v88
	v_mov_b32_e32 v101, v80
	v_pk_mul_f32 v[102:103], v[102:103], v[102:103]
	v_and_b32_e32 v83, 0xffff0000, v61
	v_and_b32_e32 v73, 0xffff0000, v73
	v_pk_fma_f32 v[100:101], v[100:101], v[100:101], v[102:103]
	v_mov_b32_e32 v102, v72
	v_mov_b32_e32 v103, v82
	v_lshlrev_b32_e32 v84, 16, v58
	v_lshlrev_b32_e32 v90, 16, v70
	v_pk_fma_f32 v[100:101], v[102:103], v[102:103], v[100:101]
	v_mov_b32_e32 v102, v73
	v_mov_b32_e32 v103, v83
	v_and_b32_e32 v85, 0xffff0000, v58
	v_and_b32_e32 v91, 0xffff0000, v70
	v_pk_fma_f32 v[100:101], v[102:103], v[102:103], v[100:101]
	v_mov_b32_e32 v102, v90
	v_mov_b32_e32 v103, v84
	v_lshlrev_b32_e32 v86, 16, v59
	v_lshlrev_b32_e32 v70, 16, v71
	v_pk_fma_f32 v[100:101], v[102:103], v[102:103], v[100:101]
	v_mov_b32_e32 v102, v91
	v_mov_b32_e32 v103, v85
	v_and_b32_e32 v87, 0xffff0000, v59
	v_and_b32_e32 v71, 0xffff0000, v71
	v_pk_fma_f32 v[100:101], v[102:103], v[102:103], v[100:101]
	v_mov_b32_e32 v102, v70
	v_mov_b32_e32 v103, v86
	v_lshlrev_b32_e32 v60, 16, v54
	v_lshlrev_b32_e32 v92, 16, v68
	v_pk_fma_f32 v[100:101], v[102:103], v[102:103], v[100:101]
	v_mov_b32_e32 v102, v71
	v_mov_b32_e32 v103, v87
	v_and_b32_e32 v61, 0xffff0000, v54
	v_and_b32_e32 v93, 0xffff0000, v68
	v_pk_fma_f32 v[100:101], v[102:103], v[102:103], v[100:101]
	v_mov_b32_e32 v102, v92
	v_mov_b32_e32 v103, v60
	v_lshlrev_b32_e32 v58, 16, v55
	v_lshlrev_b32_e32 v68, 16, v69
	v_pk_fma_f32 v[100:101], v[102:103], v[102:103], v[100:101]
	v_mov_b32_e32 v102, v93
	v_mov_b32_e32 v103, v61
	v_and_b32_e32 v59, 0xffff0000, v55
	v_lshlrev_b32_e32 v54, 16, v52
	v_and_b32_e32 v55, 0xffff0000, v52
	v_and_b32_e32 v69, 0xffff0000, v69
	v_lshlrev_b32_e32 v94, 16, v66
	v_and_b32_e32 v95, 0xffff0000, v66
	v_pk_fma_f32 v[100:101], v[102:103], v[102:103], v[100:101]
	v_mov_b32_e32 v102, v68
	v_mov_b32_e32 v103, v58
	v_pk_mul_f32 v[96:97], v[54:55], v[54:55]
	v_pk_mul_f32 v[104:105], v[94:95], v[94:95]
	v_pk_fma_f32 v[100:101], v[102:103], v[102:103], v[100:101]
	v_mov_b32_e32 v102, v69
	v_mov_b32_e32 v103, v59
	v_lshlrev_b32_e32 v52, 16, v53
	v_and_b32_e32 v53, 0xffff0000, v53
	v_lshlrev_b32_e32 v66, 16, v67
	v_and_b32_e32 v67, 0xffff0000, v67
	v_pk_fma_f32 v[100:101], v[102:103], v[102:103], v[100:101]
	v_mov_b32_e32 v102, v104
	v_mov_b32_e32 v103, v96
	v_pk_mul_f32 v[98:99], v[52:53], v[52:53]
	v_pk_add_f32 v[100:101], v[102:103], v[100:101]
	v_pk_mul_f32 v[102:103], v[66:67], v[66:67]
	v_mov_b32_e32 v96, v105
	v_pk_add_f32 v[96:97], v[96:97], v[100:101]
	v_mov_b32_e32 v100, v102
	v_mov_b32_e32 v101, v98
	v_pk_add_f32 v[96:97], v[100:101], v[96:97]
	v_mov_b32_e32 v98, v103
	v_pk_add_f32 v[96:97], v[98:99], v[96:97]
	v_mov_b32_e32 v99, v97
	v_mov_b32_e32 v98, v96
	s_nop 1
	v_permlane32_swap_b32 v97, v99
	v_permlane32_swap_b32 v96, v98
	v_lshlrev_b32_e32 v108, 16, v40
	v_and_b32_e32 v109, 0xffff0000, v40
	v_lshlrev_b32_e32 v110, 16, v41
	v_and_b32_e32 v111, 0xffff0000, v41
	s_waitcnt lgkmcnt(0)
	v_pk_add_f32 v[96:97], v[96:97], v[98:99]
	v_mov_b32_e32 v99, v97
	v_mov_b32_e32 v98, v96
	s_nop 1
	v_permlane16_swap_b32 v97, v99
	v_permlane16_swap_b32 v96, v98
	v_lshlrev_b32_e32 v112, 16, v38
	v_and_b32_e32 v113, 0xffff0000, v38
	v_lshlrev_b32_e32 v114, 16, v39
	v_and_b32_e32 v115, 0xffff0000, v39
	s_waitcnt lgkmcnt(0)
	v_pk_add_f32 v[96:97], v[96:97], v[98:99]
	s_nop 1
	v_mov_b32_dpp v99, v97 row_ror:8 row_mask:0xf bank_mask:0xf
	v_mov_b32_dpp v98, v96 row_ror:8 row_mask:0xf bank_mask:0xf
	v_lshlrev_b32_e32 v64, 16, v56
	v_and_b32_e32 v65, 0xffff0000, v56
	v_pk_mul_f32 v[116:117], v[16:17], 0.5 op_sel_hi:[1,0]
	v_lshlrev_b32_e32 v62, 16, v57
	s_waitcnt lgkmcnt(0)
	v_pk_add_f32 v[96:97], v[96:97], v[98:99]
	s_nop 1
	v_mov_b32_dpp v99, v97 row_shl:4 row_mask:0xf bank_mask:0x5
	v_mov_b32_dpp v98, v96 row_shl:4 row_mask:0xf bank_mask:0x5
	v_mov_b32_dpp v99, v97 row_shr:4 row_mask:0xf bank_mask:0xa
	v_mov_b32_dpp v98, v96 row_shr:4 row_mask:0xf bank_mask:0xa
	v_and_b32_e32 v63, 0xffff0000, v57
	v_lshlrev_b32_e32 v104, 16, v46
	v_and_b32_e32 v105, 0xffff0000, v46
	v_lshlrev_b32_e32 v46, 16, v47
	s_waitcnt lgkmcnt(0)
	v_pk_add_f32 v[96:97], v[96:97], v[98:99]
	s_nop 1
	v_mov_b32_dpp v99, v97 quad_perm:[2,3,0,1] row_mask:0xf bank_mask:0xf
	v_mov_b32_dpp v98, v96 quad_perm:[2,3,0,1] row_mask:0xf bank_mask:0xf
	v_and_b32_e32 v47, 0xffff0000, v47
	v_lshlrev_b32_e32 v56, 16, v50
	v_and_b32_e32 v57, 0xffff0000, v50
	v_lshlrev_b32_e32 v50, 16, v51
	s_waitcnt lgkmcnt(0)
	v_pk_add_f32 v[96:97], v[96:97], v[98:99]
	s_nop 1
	v_mov_b32_dpp v99, v97 quad_perm:[1,0,3,2] row_mask:0xf bank_mask:0xf
	v_mov_b32_dpp v98, v96 quad_perm:[1,0,3,2] row_mask:0xf bank_mask:0xf
	v_and_b32_e32 v51, 0xffff0000, v51
	v_lshlrev_b32_e32 v106, 16, v42
	v_and_b32_e32 v107, 0xffff0000, v42
	v_lshlrev_b32_e32 v42, 16, v43
	s_waitcnt lgkmcnt(0)
	v_pk_add_f32 v[40:41], v[96:97], v[98:99]
	v_and_b32_e32 v43, 0xffff0000, v43
	v_pk_fma_f32 v[40:41], v[40:41], s[10:11], v[36:37] op_sel_hi:[1,0,0]
	v_lshlrev_b32_e32 v100, 16, v48
	v_mul_f32_e32 v38, 0x4b800000, v41
	v_cmp_gt_f32_e32 vcc, s13, v41
	v_cmp_gt_f32_e64 s[0:1], s13, v40
	v_and_b32_e32 v101, 0xffff0000, v48
	v_cndmask_b32_e32 v38, v41, v38, vcc
	v_mul_f32_e32 v41, 0x4b800000, v40
	v_rsq_f32_e32 v38, v38
	v_cndmask_b32_e64 v40, v40, v41, s[0:1]
	v_rsq_f32_e32 v40, v40
	v_lshlrev_b32_e32 v48, 16, v49
	v_mul_f32_e32 v39, 0x45800000, v38
	v_cndmask_b32_e32 v96, v38, v39, vcc
	v_mul_f32_e32 v38, 0x45800000, v40
	v_cndmask_b32_e64 v98, v40, v38, s[0:1]
	v_pk_mul_f32 v[38:39], v[96:97], v[80:81] op_sel_hi:[0,1]
	v_pk_mul_f32 v[38:39], v[12:13], v[38:39]
	v_pk_mul_f32 v[40:41], v[96:97], v[82:83] op_sel_hi:[0,1]
	v_pk_fma_f32 v[38:39], v[116:117], v[38:39], v[64:65]
	v_pk_mul_f32 v[64:65], v[18:19], 0.5 op_sel_hi:[1,0]
	v_pk_mul_f32 v[40:41], v[14:15], v[40:41]
	v_and_b32_e32 v49, 0xffff0000, v49
	v_pk_fma_f32 v[40:41], v[64:65], v[40:41], v[62:63]
	global_store_dwordx4 v[32:33], v[38:41], off offset:-4096
	v_lshlrev_b32_e32 v102, 16, v44
	v_and_b32_e32 v103, 0xffff0000, v44
	v_pk_mul_f32 v[38:39], v[98:99], v[88:89] op_sel_hi:[0,1]
	v_pk_mul_f32 v[40:41], v[98:99], v[72:73] op_sel_hi:[0,1]
	v_pk_mul_f32 v[38:39], v[12:13], v[38:39]
	v_pk_mul_f32 v[40:41], v[14:15], v[40:41]
	v_pk_fma_f32 v[38:39], v[116:117], v[38:39], v[104:105]
	v_pk_fma_f32 v[40:41], v[64:65], v[40:41], v[46:47]
	global_store_dwordx4 v[32:33], v[38:41], off
	v_pk_mul_f32 v[46:47], v[20:21], 0.5 op_sel_hi:[1,0]
	v_lshlrev_b32_e32 v44, 16, v45
	v_pk_mul_f32 v[38:39], v[96:97], v[84:85] op_sel_hi:[0,1]
	v_pk_mul_f32 v[38:39], v[8:9], v[38:39]
	v_pk_mul_f32 v[40:41], v[96:97], v[86:87] op_sel_hi:[0,1]
	v_pk_fma_f32 v[38:39], v[46:47], v[38:39], v[56:57]
	v_pk_mul_f32 v[56:57], v[22:23], 0.5 op_sel_hi:[1,0]
	v_pk_mul_f32 v[40:41], v[10:11], v[40:41]
	v_and_b32_e32 v45, 0xffff0000, v45
	v_pk_fma_f32 v[40:41], v[56:57], v[40:41], v[50:51]
	global_store_dwordx4 v[32:33], v[38:41], off offset:-3072
	v_add_u32_e32 v148, 2, v148
	v_cmp_ge_i32_e32 vcc, v148, v186
	v_pk_mul_f32 v[38:39], v[98:99], v[90:91] op_sel_hi:[0,1]
	v_pk_mul_f32 v[40:41], v[98:99], v[70:71] op_sel_hi:[0,1]
	v_pk_mul_f32 v[38:39], v[8:9], v[38:39]
	v_pk_mul_f32 v[40:41], v[10:11], v[40:41]
	v_pk_fma_f32 v[38:39], v[46:47], v[38:39], v[106:107]
	v_pk_fma_f32 v[40:41], v[56:57], v[40:41], v[42:43]
	global_store_dwordx4 v[32:33], v[38:41], off offset:1024
	v_pk_mul_f32 v[42:43], v[24:25], 0.5 op_sel_hi:[1,0]
	v_pk_mul_f32 v[46:47], v[26:27], 0.5 op_sel_hi:[1,0]
	v_pk_mul_f32 v[38:39], v[96:97], v[60:61] op_sel_hi:[0,1]
	v_pk_mul_f32 v[40:41], v[96:97], v[58:59] op_sel_hi:[0,1]
	v_pk_mul_f32 v[38:39], v[4:5], v[38:39]
	v_pk_mul_f32 v[40:41], v[6:7], v[40:41]
	v_pk_fma_f32 v[38:39], v[42:43], v[38:39], v[100:101]
	v_pk_fma_f32 v[40:41], v[46:47], v[40:41], v[48:49]
	global_store_dwordx4 v[32:33], v[38:41], off offset:-2048
	s_or_b64 s[6:7], vcc, s[6:7]
	s_nop 0
	v_pk_mul_f32 v[38:39], v[98:99], v[92:93] op_sel_hi:[0,1]
	v_pk_mul_f32 v[40:41], v[98:99], v[68:69] op_sel_hi:[0,1]
	v_pk_mul_f32 v[38:39], v[4:5], v[38:39]
	v_pk_mul_f32 v[40:41], v[6:7], v[40:41]
	v_pk_fma_f32 v[38:39], v[42:43], v[38:39], v[108:109]
	v_pk_fma_f32 v[40:41], v[46:47], v[40:41], v[110:111]
	global_store_dwordx4 v[32:33], v[38:41], off offset:2048
	v_pk_mul_f32 v[42:43], v[28:29], 0.5 op_sel_hi:[1,0]
	v_pk_mul_f32 v[46:47], v[30:31], 0.5 op_sel_hi:[1,0]
	v_pk_mul_f32 v[38:39], v[96:97], v[54:55] op_sel_hi:[0,1]
	v_pk_mul_f32 v[40:41], v[96:97], v[52:53] op_sel_hi:[0,1]
	v_pk_mul_f32 v[38:39], v[0:1], v[38:39]
	v_pk_mul_f32 v[40:41], v[2:3], v[40:41]
	v_pk_fma_f32 v[38:39], v[42:43], v[38:39], v[102:103]
	v_pk_fma_f32 v[40:41], v[46:47], v[40:41], v[44:45]
	global_store_dwordx4 v[32:33], v[38:41], off offset:-1024
	s_nop 1
	v_pk_mul_f32 v[38:39], v[98:99], v[94:95] op_sel_hi:[0,1]
	v_pk_mul_f32 v[40:41], v[98:99], v[66:67] op_sel_hi:[0,1]
	v_pk_mul_f32 v[38:39], v[0:1], v[38:39]
	v_pk_mul_f32 v[40:41], v[2:3], v[40:41]
	v_pk_fma_f32 v[38:39], v[42:43], v[38:39], v[112:113]
	v_pk_fma_f32 v[40:41], v[46:47], v[40:41], v[114:115]
	global_store_dwordx4 v[32:33], v[38:41], off offset:3072
	v_lshl_add_u64 v[32:33], v[32:33], 0, s[2:3]
	s_andn2_b64 exec, exec, s[6:7]
	s_cbranch_execz .LBB0_1213
.LBB0_1211:
	v_add_u32_e32 v62, 0xffffe000, v148
	v_ashrrev_i32_e32 v62, 12, v62
	v_add_u32_e32 v62, 1, v62
	v_cmp_lt_i32_e32 vcc, s12, v148
	s_nop 1
	v_cndmask_b32_e32 v62, 0, v62, vcc
	v_cmp_ne_u32_e32 vcc, v62, v79
	s_and_saveexec_b64 s[0:1], vcc
	s_cbranch_execz .LBB0_1210
	v_mul_i32_i24_e32 v16, 0x2400, v62
	v_ashrrev_i32_e32 v17, 31, v16
	v_lshl_add_u64 v[16:17], v[16:17], 2, s[34:35]
	v_lshl_add_u64 v[24:25], v[16:17], 0, s[8:9]
	v_mov_b32_e32 v155, v145
	v_mov_b32_e32 v153, v145
	v_lshl_add_u64 v[26:27], v[24:25], 0, v[144:145]
	v_lshl_add_u64 v[28:29], v[24:25], 0, v[154:155]
	v_lshl_add_u64 v[64:65], v[24:25], 0, v[152:153]
	v_mov_b32_e32 v151, v145
	global_load_dwordx4 v[16:19], v[26:27], off
	global_load_dwordx4 v[20:23], v[28:29], off
	v_lshl_add_u64 v[80:81], v[24:25], 0, v[150:151]
	global_load_dwordx4 v[24:27], v[64:65], off
	global_load_dwordx4 v[28:31], v[80:81], off
	v_mov_b32_e32 v79, v62
	s_branch .LBB0_1210
